# attn: K/V prefetch register rotation before the new loads (no wait on fresh loads)
# baseline (speedup 1.0000x reference)
; #define LOAD_TILE(ti, kreg, vreg) do { const int k0_ = TILE_K0(ti); const size_t grow_ = ((ti) < 4) ? (size_t)(M_ + b * LCTX + k0_) : (size_t)(b * SEQ + k0_); \
;         kreg = *(const u32x4*)(QKV + (grow_ + krow) * NQKV + 1024 + kvh * 64 + 8 * kch); vreg = *(const u32x4*)(QKV + (grow_ + lane) * NQKV + 1280 + kvh * 64 + 8 * w); } while (0)
; #define LOAD_TILE(ti, kreg, vreg) do { const int k0_ = TILE_K0(ti); const size_t grow_ = ((ti) < 4) ? (size_t)(M_ + b * LCTX + k0_) : (size_t)(b * SEQ + k0_); \
;         kreg = *(const u32x4*)(QKV + (grow_ + krow) * NQKV + 1024 + kvh * 64 + 8 * kch); vreg = *(const u32x4*)(QKV + (grow_ + lane) * NQKV + 1280 + kvh * 64 + 8 * w); } while (0)
; #define STAGE_NEXT(ti, vnext) do { if ((ti) + 1 < ntiles) STORE_TILE(((ti) + 1) & 1, vnext); \
;         kreg = kreg2; vreg = vreg2; kreg2 = kreg3; vreg2 = vreg3; \
;         if ((ti) + 4 < ntiles) LOAD_TILE((ti) + 4, kreg3, vreg3); } while (0)
;     ...
;         bf16x8 pa[4];
;         LOAD_TILE(0, kreg, vreg); STORE_TILE(0, 0); LOAD_TILE(1, kreg, vreg); LOAD_TILE(2, kreg2, vreg2); LOAD_TILE(3, kreg3, vreg3); __syncthreads();
;         {
;             QK_MAX(0, 0)
;             EXP_PACK();
;             if (resc) { _Pragma("unroll") for (int r = 0; r < 16; ++r) { o0[r] *= fres; o1[r] *= fres; } }
;             STAGE_NEXT(0, 1);
;             __syncthreads();
;         }
;         int vprev = 0, vcur = 1;
; #pragma unroll 1
;         for (int ti = 1; ti < ntiles; ++ti) {
;             const int vnext = (vcur == 2) ? 0 : vcur + 1;
;             QK_MAX(ti, ti & 1)
;             PV_TILE(vprev);
;             EXP_PACK();
; #pragma unroll
;             for (int i_ = 0; i_ < 8; ++i_) { __builtin_amdgcn_sched_group_barrier(0x008, 1, 0); __builtin_amdgcn_sched_group_barrier(0x002, 11, 0); }
;             if (resc) { _Pragma("unroll") for (int r = 0; r < 16; ++r) { o0[r] *= fres; o1[r] *= fres; } }
;             STAGE_NEXT(ti, vnext);
;             vprev = vcur; vcur = vnext;
;             __syncthreads();
.LBB0_521:
	s_cmp_gt_i32 s8, s58
	s_waitcnt vmcnt(0)
	v_mov_b64_e32 v[110:111], v[90:91]
	v_mov_b64_e32 v[106:107], v[94:95]
	v_mov_b64_e32 v[108:109], v[88:89]
	v_mov_b64_e32 v[104:105], v[92:93]
	v_mov_b64_e32 v[88:89], v[116:117]
	v_mov_b64_e32 v[92:93], v[112:113]
	v_mov_b64_e32 v[90:91], v[118:119]
	v_mov_b64_e32 v[94:95], v[114:115]
	s_cbranch_scc1 .LBB0_523
	s_ashr_i32 s25, s24, 31
	v_lshl_add_u64 v[226:227], s[24:25], 0, v[154:155]
	v_mad_u64_u32 v[230:231], s[40:41], v226, s46, v[172:173]
	v_mad_i32_i24 v231, v227, s46, v231
	v_or_b32_e32 v232, s24, v144
	v_mov_b64_e32 v[226:227], s[22:23]
	v_mad_i64_i32 v[226:227], s[40:41], v232, s46, v[226:227]
	global_load_dwordx4 v[116:119], v[230:231], off offset:2048
	global_load_dwordx4 v[112:115], v[226:227], off offset:2560
.LBB0_523:
	v_exp_f32_e32 v48, v48
	v_exp_f32_e32 v64, v64
	v_exp_f32_e32 v49, v49
	v_exp_f32_e32 v65, v65
	v_exp_f32_e32 v50, v50
	v_exp_f32_e32 v66, v66
	v_exp_f32_e32 v51, v51
	v_exp_f32_e32 v67, v67
	v_add_f32_e32 v233, v48, v64
	v_exp_f32_e32 v52, v52
	v_exp_f32_e32 v68, v68
	v_add_f32_e32 v234, v49, v65
	v_exp_f32_e32 v53, v53
	v_exp_f32_e32 v69, v69
	v_cvt_pk_bf16_f32 v132, v48, v49
	v_add_f32_e32 v48, 0, v233
	v_add_f32_e32 v235, v50, v66
	v_exp_f32_e32 v54, v54
	v_exp_f32_e32 v70, v70
	v_add_f32_e32 v48, v234, v48
	v_add_f32_e32 v236, v51, v67
	v_exp_f32_e32 v55, v55
	v_exp_f32_e32 v71, v71
	v_add_f32_e32 v48, v235, v48
	v_add_f32_e32 v237, v52, v68
	v_exp_f32_e32 v56, v56
	v_exp_f32_e32 v72, v72
	v_add_f32_e32 v48, v236, v48
	v_add_f32_e32 v238, v53, v69
	v_exp_f32_e32 v57, v57
	v_exp_f32_e32 v73, v73
	v_add_f32_e32 v48, v237, v48
	v_add_f32_e32 v239, v54, v70
	v_exp_f32_e32 v58, v58
	v_exp_f32_e32 v74, v74
	v_add_f32_e32 v48, v238, v48
	v_add_f32_e32 v240, v55, v71
	v_exp_f32_e32 v59, v59
	v_exp_f32_e32 v75, v75
	v_add_f32_e32 v48, v239, v48
	v_add_f32_e32 v153, v56, v72
	v_exp_f32_e32 v60, v60
	v_exp_f32_e32 v76, v76
	v_add_f32_e32 v48, v240, v48
	v_add_f32_e32 v182, v57, v73
	v_exp_f32_e32 v61, v61
	v_exp_f32_e32 v77, v77
	v_add_f32_e32 v48, v153, v48
	v_add_f32_e32 v183, v58, v74
	v_exp_f32_e32 v62, v62
	v_exp_f32_e32 v78, v78
	v_add_f32_e32 v48, v182, v48
	v_add_f32_e32 v184, v59, v75
	v_exp_f32_e32 v63, v63
	v_exp_f32_e32 v79, v79
	v_add_f32_e32 v48, v183, v48
	v_add_f32_e32 v185, v60, v76
	v_add_f32_e32 v48, v184, v48
	v_add_f32_e32 v186, v61, v77
	v_add_f32_e32 v48, v185, v48
	v_add_f32_e32 v187, v62, v78
	v_add_f32_e32 v48, v186, v48
	v_add_f32_e32 v188, v63, v79
	v_add_f32_e32 v48, v187, v48
	v_add_f32_e32 v48, v188, v48
	s_add_i32 s24, s24, 64
	v_cvt_pk_bf16_f32 v133, v50, v51
	v_cvt_pk_bf16_f32 v134, v52, v53
	v_cvt_pk_bf16_f32 v135, v54, v55
	v_cvt_pk_bf16_f32 v128, v56, v57
	v_cvt_pk_bf16_f32 v129, v58, v59
	v_cvt_pk_bf16_f32 v130, v60, v61
	v_cvt_pk_bf16_f32 v131, v62, v63
	v_cvt_pk_bf16_f32 v124, v64, v65
	v_cvt_pk_bf16_f32 v125, v66, v67
	v_cvt_pk_bf16_f32 v126, v68, v69
	v_cvt_pk_bf16_f32 v127, v70, v71
	v_cvt_pk_bf16_f32 v120, v72, v73
	v_cvt_pk_bf16_f32 v121, v74, v75
	v_cvt_pk_bf16_f32 v122, v76, v77
	v_cvt_pk_bf16_f32 v123, v78, v79
	v_add_f32_e32 v165, v165, v48
	s_cmp_eq_u32 s13, s8
	v_subrev_u32_e32 v167, 64, v167
	s_waitcnt lgkmcnt(0)
	s_barrier
	s_cbranch_scc1 .LBB0_502
	s_mov_b32 s25, s8
	s_mov_b32 s62, s59
	s_branch .LBB0_507
